# FFN-in: first K-loop iteration of units 2+ peeled with vmcnt(16) on its first two waits (previous epilogue stores no longer forced complete early)
# speedup vs baseline: 1.0046x; 1.0046x over previous
; #define PG8_STAGE(bufoff, gbase, voff) do { _Pragma("unroll") for (int _i = 0; _i < 2; ++_i) \
;         __builtin_amdgcn_global_load_lds((const unsigned*)((const char*)(gbase) + (voff)[_i]), (PG8_LAS unsigned*)(lds + (bufoff) + ldsw + _i * 8192), 16, 0, 0); } while (0)
; #define PG8_LDA(dst, b, h) do { _Pragma("unroll") for (int m = 0; m < 4; ++m) _Pragma("unroll") for (int k = 0; k < 2; ++k) dst[m][k] = *(const PG8_LAS bf16x8*)(lds + PG8_SA(b, h) + aoff + m * 2048 + k * 1024); } while (0)
; #define PG8_LDB(dst, b, h) do { _Pragma("unroll") for (int n = 0; n < 2; ++n) _Pragma("unroll") for (int k = 0; k < 2; ++k) dst[n][k] = *(const PG8_LAS bf16x8*)(lds + PG8_SB(b, h) + boff + n * 2048 + k * 1024); } while (0)
; #define PG8_MMA(ai, bj, At, Bt) do { __builtin_amdgcn_s_setprio(1); _Pragma("unroll") for (int m = 0; m < 4; ++m) _Pragma("unroll") for (int n = 0; n < 2; ++n) _Pragma("unroll") for (int k = 0; k < 2; ++k) \
;         acc[ai][bj][m][n] = __builtin_amdgcn_mfma_f32_16x16x32_bf16(Bt[n][k], At[m][k], acc[ai][bj][m][n], 0, 0, 0); __builtin_amdgcn_s_setprio(0); } while (0)
; #define PG8_WAIT_V(n) asm volatile("s_waitcnt vmcnt(" #n ")" ::: "memory")
; #define PG8_WAIT_L(n) asm volatile("s_waitcnt lgkmcnt(" #n ")" ::: "memory")
; #define PG8_BAR __builtin_amdgcn_s_barrier()
; #define PG8_SCHED __builtin_amdgcn_sched_barrier(0)
; template <class Epi, class Sched, bool ALIGN_EPI = false, bool SP2 = false>
; __device__ __forceinline__ void gemm_phase(PG8_LAS unsigned char* lds, const Gemm g, const Sched& S, const Epi& E) {
;     ...
;             PG8_LDB(B0, 0, 0); PG8_LDB(B1, 0, 1); PG8_SCHED; PG8_LDA(At, 0, 0); PG8_STAGE(PG8_SA(1, 1), a1 + hstep, voffA);
;             PG8_WAIT_V(8); PG8_WAIT_L(0); PG8_BAR; PG8_MMA(0, 0, At, B0); PG8_MMA(0, 1, At, B1); PG8_BAR; PG8_SCHED;
;     ...
;         for (int a = 0; a < 2; ++a)
; #pragma unroll
;             for (int b = 0; b < 2; ++b)
; #pragma unroll
;                 for (int m = 0; m < 4; ++m)
; #pragma unroll
;                     for (int n = 0; n < 2; ++n) acc[a][b][m][n] = (f32x4){0.f, 0.f, 0.f, 0.f};
.LBB0_109:
	s_ashr_i32 s17, s16, 31
	s_lshl_b64 s[18:19], s[16:17], 19
	s_add_u32 s18, s30, s18
	s_addc_u32 s19, s31, s19
	s_and_b64 s[42:43], s[4:5], exec
	s_cselect_b32 s17, s19, s45
	s_cselect_b32 s62, s18, s44
	s_ashr_i32 s15, s14, 31
	s_lshl_b64 s[42:43], s[14:15], 19
	s_add_u32 s42, s20, s42
	s_addc_u32 s43, s38, s43
	s_and_b64 s[48:49], s[4:5], exec
	s_cselect_b32 s15, s43, s47
	s_cselect_b32 s63, s42, s46
	s_add_u32 s44, s44, 0x40080
	s_addc_u32 s45, s45, 0
	s_add_u32 s64, s46, 0x100
	v_mov_b32_e32 v0, 0
	s_addc_u32 s65, s47, 0
	s_mov_b32 s66, -2
	v_mov_b32_e32 v1, v0
	v_mov_b32_e32 v2, v0
	v_mov_b32_e32 v3, v0
	v_mov_b32_e32 v8, v0
	v_mov_b32_e32 v9, v0
	v_mov_b32_e32 v10, v0
	v_mov_b32_e32 v11, v0
	v_mov_b32_e32 v16, v0
	v_mov_b32_e32 v17, v0
	v_mov_b32_e32 v18, v0
	v_mov_b32_e32 v19, v0
	v_mov_b32_e32 v24, v0
	v_mov_b32_e32 v25, v0
	v_mov_b32_e32 v26, v0
	v_mov_b32_e32 v27, v0
	v_mov_b32_e32 v32, v0
	v_mov_b32_e32 v33, v0
	v_mov_b32_e32 v34, v0
	v_mov_b32_e32 v35, v0
	v_mov_b32_e32 v40, v0
	v_mov_b32_e32 v41, v0
	v_mov_b32_e32 v42, v0
	v_mov_b32_e32 v43, v0
	v_mov_b32_e32 v48, v0
	v_mov_b32_e32 v49, v0
	v_mov_b32_e32 v50, v0
	v_mov_b32_e32 v51, v0
	v_mov_b32_e32 v56, v0
	v_mov_b32_e32 v57, v0
	v_mov_b32_e32 v58, v0
	v_mov_b32_e32 v59, v0
	v_mov_b32_e32 v4, v0
	v_mov_b32_e32 v5, v0
	v_mov_b32_e32 v6, v0
	v_mov_b32_e32 v7, v0
	v_mov_b32_e32 v12, v0
	v_mov_b32_e32 v13, v0
	v_mov_b32_e32 v14, v0
	v_mov_b32_e32 v15, v0
	v_mov_b32_e32 v20, v0
	v_mov_b32_e32 v21, v0
	v_mov_b32_e32 v22, v0
	v_mov_b32_e32 v23, v0
	v_mov_b32_e32 v28, v0
	v_mov_b32_e32 v29, v0
	v_mov_b32_e32 v30, v0
	v_mov_b32_e32 v31, v0
	v_mov_b32_e32 v36, v0
	v_mov_b32_e32 v37, v0
	v_mov_b32_e32 v38, v0
	v_mov_b32_e32 v39, v0
	v_mov_b32_e32 v44, v0
	v_mov_b32_e32 v45, v0
	v_mov_b32_e32 v46, v0
	v_mov_b32_e32 v47, v0
	v_mov_b32_e32 v52, v0
	v_mov_b32_e32 v53, v0
	v_mov_b32_e32 v54, v0
	v_mov_b32_e32 v55, v0
	v_mov_b32_e32 v60, v0
	v_mov_b32_e32 v61, v0
	v_mov_b32_e32 v62, v0
	v_mov_b32_e32 v63, v0
	v_mov_b32_e32 v64, v0
	v_mov_b32_e32 v65, v0
	v_mov_b32_e32 v66, v0
	v_mov_b32_e32 v67, v0
	v_mov_b32_e32 v72, v0
	v_mov_b32_e32 v73, v0
	v_mov_b32_e32 v74, v0
	v_mov_b32_e32 v75, v0
	v_mov_b32_e32 v82, v0
	v_mov_b32_e32 v83, v0
	v_mov_b32_e32 v84, v0
	v_mov_b32_e32 v85, v0
	v_mov_b32_e32 v90, v0
	v_mov_b32_e32 v91, v0
	v_mov_b32_e32 v92, v0
	v_mov_b32_e32 v93, v0
	v_mov_b32_e32 v98, v0
	v_mov_b32_e32 v99, v0
	v_mov_b32_e32 v100, v0
	v_mov_b32_e32 v101, v0
	v_mov_b32_e32 v106, v0
	v_mov_b32_e32 v107, v0
	v_mov_b32_e32 v108, v0
	v_mov_b32_e32 v109, v0
	v_mov_b32_e32 v114, v0
	v_mov_b32_e32 v115, v0
	v_mov_b32_e32 v116, v0
	v_mov_b32_e32 v117, v0
	v_mov_b32_e32 v122, v0
	v_mov_b32_e32 v123, v0
	v_mov_b32_e32 v124, v0
	v_mov_b32_e32 v125, v0
	v_mov_b32_e32 v68, v0
	v_mov_b32_e32 v69, v0
	v_mov_b32_e32 v70, v0
	v_mov_b32_e32 v71, v0
	v_mov_b32_e32 v76, v0
	v_mov_b32_e32 v77, v0
	v_mov_b32_e32 v78, v0
	v_mov_b32_e32 v79, v0
	v_mov_b32_e32 v86, v0
	v_mov_b32_e32 v87, v0
	v_mov_b32_e32 v88, v0
	v_mov_b32_e32 v89, v0
	v_mov_b32_e32 v94, v0
	v_mov_b32_e32 v95, v0
	v_mov_b32_e32 v96, v0
	v_mov_b32_e32 v97, v0
	v_mov_b32_e32 v102, v0
	v_mov_b32_e32 v103, v0
	v_mov_b32_e32 v104, v0
	v_mov_b32_e32 v105, v0
	v_mov_b32_e32 v110, v0
	v_mov_b32_e32 v111, v0
	v_mov_b32_e32 v112, v0
	v_mov_b32_e32 v113, v0
	v_mov_b32_e32 v118, v0
	v_mov_b32_e32 v119, v0
	v_mov_b32_e32 v120, v0
	v_mov_b32_e32 v121, v0
	v_mov_b32_e32 v126, v0
	v_mov_b32_e32 v127, v0
	v_mov_b32_e32 v128, v0
	v_mov_b32_e32 v129, v0
	s_cmp_eq_u32 s58, 1
	s_cbranch_scc1 .LBB0_110
	s_add_u32 s46, s44, 0xfffc0080
	s_addc_u32 s47, s45, -1
	s_add_i32 s67, 0, 0x10000
	s_cmp_eq_u32 s66, 12
	s_cselect_b32 s49, s17, s47
	s_cselect_b32 s48, s62, s46
	v_add_u32_e32 v145, s67, v143
	s_cselect_b32 s47, s15, s65
	s_cselect_b32 s46, s63, s64
	s_add_i32 s70, 0, 0x14000
	ds_read_b128 v[146:149], v145
	ds_read_b128 v[150:153], v145 offset:1024
	ds_read_b128 v[154:157], v145 offset:2048
	ds_read_b128 v[158:161], v145 offset:3072
	v_add_u32_e32 v145, s70, v143
	ds_read_b128 v[176:179], v145
	ds_read_b128 v[180:183], v145 offset:1024
	ds_read_b128 v[184:187], v145 offset:2048
	ds_read_b128 v[188:191], v145 offset:3072
	v_lshl_add_u64 v[200:201], s[44:45], 0, v[138:139]
	s_add_i32 m0, s50, 0xc000
	ds_read_b128 v[192:195], v144
	ds_read_b128 v[196:199], v144 offset:1024
	ds_read_b128 v[208:211], v144 offset:2048
	ds_read_b128 v[212:215], v144 offset:3072
	ds_read_b128 v[216:219], v144 offset:4096
	ds_read_b128 v[220:223], v144 offset:5120
	ds_read_b128 v[224:227], v144 offset:6144
	ds_read_b128 v[228:231], v144 offset:7168
	global_load_lds_dwordx4 v[200:201], off
	v_lshl_add_u64 v[200:201], s[44:45], 0, v[140:141]
	s_add_i32 m0, s50, 0xe000
	s_nop 0
	global_load_lds_dwordx4 v[200:201], off
	s_waitcnt vmcnt(16)
	s_waitcnt lgkmcnt(0)
	s_barrier
; #define PG8_STAGE(bufoff, gbase, voff) do { _Pragma("unroll") for (int _i = 0; _i < 2; ++_i) \
;         __builtin_amdgcn_global_load_lds((const unsigned*)((const char*)(gbase) + (voff)[_i]), (PG8_LAS unsigned*)(lds + (bufoff) + ldsw + _i * 8192), 16, 0, 0); } while (0)
; #define PG8_LDA(dst, b, h) do { _Pragma("unroll") for (int m = 0; m < 4; ++m) _Pragma("unroll") for (int k = 0; k < 2; ++k) dst[m][k] = *(const PG8_LAS bf16x8*)(lds + PG8_SA(b, h) + aoff + m * 2048 + k * 1024); } while (0)
; #define PG8_MMA(ai, bj, At, Bt) do { __builtin_amdgcn_s_setprio(1); _Pragma("unroll") for (int m = 0; m < 4; ++m) _Pragma("unroll") for (int n = 0; n < 2; ++n) _Pragma("unroll") for (int k = 0; k < 2; ++k) \
;         acc[ai][bj][m][n] = __builtin_amdgcn_mfma_f32_16x16x32_bf16(Bt[n][k], At[m][k], acc[ai][bj][m][n], 0, 0, 0); __builtin_amdgcn_s_setprio(0); } while (0)
; #define PG8_WAIT_V(n) asm volatile("s_waitcnt vmcnt(" #n ")" ::: "memory")
; #define PG8_WAIT_L(n) asm volatile("s_waitcnt lgkmcnt(" #n ")" ::: "memory")
; #define PG8_BAR __builtin_amdgcn_s_barrier()
; #define PG8_SCHED __builtin_amdgcn_sched_barrier(0)
; template <class Epi, class Sched, bool ALIGN_EPI = false, bool SP2 = false>
; __device__ __forceinline__ void gemm_phase(PG8_LAS unsigned char* lds, const Gemm g, const Sched& S, const Epi& E) {
;     ...
;             PG8_WAIT_V(8); PG8_WAIT_L(0); PG8_BAR; PG8_MMA(0, 0, At, B0); PG8_MMA(0, 1, At, B1); PG8_BAR; PG8_SCHED;
;             PG8_LDA(At, 0, 1); PG8_STAGE(PG8_SB(0, 0), b2, voffB); PG8_STAGE(PG8_SB(0, 1), b2 + hstep, voffB); PG8_STAGE(PG8_SA(0, 0), a2, voffA);
;             PG8_WAIT_V(8); PG8_WAIT_L(0); PG8_BAR; PG8_MMA(1, 0, At, B0); PG8_MMA(1, 1, At, B1); PG8_BAR; PG8_SCHED;
	s_setprio 1
	s_waitcnt lgkmcnt(0)
	v_mfma_f32_16x16x32_bf16 v[126:129], v[146:149], v[192:195], v[126:129]
	v_mfma_f32_16x16x32_bf16 v[118:121], v[154:157], v[192:195], v[118:121]
	v_mfma_f32_16x16x32_bf16 v[110:113], v[146:149], v[208:211], v[110:113]
	v_mfma_f32_16x16x32_bf16 v[102:105], v[154:157], v[208:211], v[102:105]
	v_mfma_f32_16x16x32_bf16 v[94:97], v[146:149], v[216:219], v[94:97]
	v_mfma_f32_16x16x32_bf16 v[86:89], v[154:157], v[216:219], v[86:89]
	v_mfma_f32_16x16x32_bf16 v[76:79], v[146:149], v[224:227], v[76:79]
	v_mfma_f32_16x16x32_bf16 v[68:71], v[154:157], v[224:227], v[68:71]
	v_mfma_f32_16x16x32_bf16 v[126:129], v[150:153], v[196:199], v[126:129]
	v_mfma_f32_16x16x32_bf16 v[118:121], v[158:161], v[196:199], v[118:121]
	v_mfma_f32_16x16x32_bf16 v[110:113], v[150:153], v[212:215], v[110:113]
	v_mfma_f32_16x16x32_bf16 v[102:105], v[158:161], v[212:215], v[102:105]
	v_mfma_f32_16x16x32_bf16 v[94:97], v[150:153], v[220:223], v[94:97]
	v_mfma_f32_16x16x32_bf16 v[86:89], v[158:161], v[220:223], v[86:89]
	v_mfma_f32_16x16x32_bf16 v[76:79], v[150:153], v[228:231], v[76:79]
	v_mfma_f32_16x16x32_bf16 v[68:71], v[158:161], v[228:231], v[68:71]
	s_setprio 0
	s_setprio 1
	v_mfma_f32_16x16x32_bf16 v[122:125], v[176:179], v[192:195], v[122:125]
	v_mfma_f32_16x16x32_bf16 v[114:117], v[184:187], v[192:195], v[114:117]
	v_mfma_f32_16x16x32_bf16 v[106:109], v[176:179], v[208:211], v[106:109]
	v_mfma_f32_16x16x32_bf16 v[98:101], v[184:187], v[208:211], v[98:101]
	v_mfma_f32_16x16x32_bf16 v[90:93], v[176:179], v[216:219], v[90:93]
	v_mfma_f32_16x16x32_bf16 v[82:85], v[184:187], v[216:219], v[82:85]
	v_mfma_f32_16x16x32_bf16 v[72:75], v[176:179], v[224:227], v[72:75]
	v_mfma_f32_16x16x32_bf16 v[64:67], v[184:187], v[224:227], v[64:67]
	v_mfma_f32_16x16x32_bf16 v[122:125], v[180:183], v[196:199], v[122:125]
	v_mfma_f32_16x16x32_bf16 v[114:117], v[188:191], v[196:199], v[114:117]
	v_mfma_f32_16x16x32_bf16 v[106:109], v[180:183], v[212:215], v[106:109]
	v_mfma_f32_16x16x32_bf16 v[98:101], v[188:191], v[212:215], v[98:101]
	v_mfma_f32_16x16x32_bf16 v[90:93], v[180:183], v[220:223], v[90:93]
	v_mfma_f32_16x16x32_bf16 v[82:85], v[188:191], v[220:223], v[82:85]
	v_mfma_f32_16x16x32_bf16 v[72:75], v[180:183], v[228:231], v[72:75]
	v_mfma_f32_16x16x32_bf16 v[64:67], v[188:191], v[228:231], v[64:67]
	s_setprio 0
	s_barrier
	s_add_i32 s67, s67, s39
	v_lshl_add_u64 v[200:201], s[46:47], 0, v[134:135]
	s_mov_b32 m0, s67
	ds_read_b128 v[192:195], v144 offset:16384
	ds_read_b128 v[196:199], v144 offset:17408
	ds_read_b128 v[208:211], v144 offset:18432
	ds_read_b128 v[212:215], v144 offset:19456
	ds_read_b128 v[216:219], v144 offset:20480
	ds_read_b128 v[220:223], v144 offset:21504
	ds_read_b128 v[224:227], v144 offset:22528
	ds_read_b128 v[228:231], v144 offset:23552
	global_load_lds_dwordx4 v[200:201], off
	s_add_i32 m0, s67, 0x2000
	s_add_u32 s68, s46, 0x40000
	v_lshl_add_u64 v[232:233], s[46:47], 0, v[130:131]
	s_addc_u32 s69, s47, 0
	s_add_i32 s67, s70, s39
	global_load_lds_dwordx4 v[232:233], off
	v_lshl_add_u64 v[234:235], s[68:69], 0, v[134:135]
	s_mov_b32 m0, s67
	v_lshl_add_u64 v[236:237], s[48:49], 0, v[132:133]
	global_load_lds_dwordx4 v[234:235], off
	v_lshl_add_u64 v[234:235], s[68:69], 0, v[130:131]
	s_add_i32 m0, s67, 0x2000
	s_nop 0
	global_load_lds_dwordx4 v[234:235], off
	v_lshl_add_u64 v[234:235], s[48:49], 0, v[136:137]
	s_mov_b32 m0, s50
	s_nop 0
	global_load_lds_dwordx4 v[234:235], off
	s_mov_b32 m0, s51
	s_nop 0
	global_load_lds_dwordx4 v[236:237], off
	s_waitcnt vmcnt(16)
	s_waitcnt lgkmcnt(0)
	s_barrier
	s_setprio 1
	s_waitcnt lgkmcnt(0)
	v_mfma_f32_16x16x32_bf16 v[60:63], v[146:149], v[192:195], v[60:63]
	v_mfma_f32_16x16x32_bf16 v[52:55], v[154:157], v[192:195], v[52:55]
	v_mfma_f32_16x16x32_bf16 v[44:47], v[146:149], v[208:211], v[44:47]
	v_mfma_f32_16x16x32_bf16 v[36:39], v[154:157], v[208:211], v[36:39]
	v_mfma_f32_16x16x32_bf16 v[28:31], v[146:149], v[216:219], v[28:31]
	v_mfma_f32_16x16x32_bf16 v[20:23], v[154:157], v[216:219], v[20:23]
	v_mfma_f32_16x16x32_bf16 v[12:15], v[146:149], v[224:227], v[12:15]
	v_mfma_f32_16x16x32_bf16 v[4:7], v[154:157], v[224:227], v[4:7]
	v_mfma_f32_16x16x32_bf16 v[60:63], v[150:153], v[196:199], v[60:63]
	v_mfma_f32_16x16x32_bf16 v[52:55], v[158:161], v[196:199], v[52:55]
	v_mfma_f32_16x16x32_bf16 v[44:47], v[150:153], v[212:215], v[44:47]
	v_mfma_f32_16x16x32_bf16 v[36:39], v[158:161], v[212:215], v[36:39]
	v_mfma_f32_16x16x32_bf16 v[28:31], v[150:153], v[220:223], v[28:31]
	v_mfma_f32_16x16x32_bf16 v[20:23], v[158:161], v[220:223], v[20:23]
	v_mfma_f32_16x16x32_bf16 v[12:15], v[150:153], v[228:231], v[12:15]
	v_mfma_f32_16x16x32_bf16 v[4:7], v[158:161], v[228:231], v[4:7]
	s_setprio 0
	s_setprio 1
	v_mfma_f32_16x16x32_bf16 v[56:59], v[176:179], v[192:195], v[56:59]
	v_mfma_f32_16x16x32_bf16 v[48:51], v[184:187], v[192:195], v[48:51]
	v_mfma_f32_16x16x32_bf16 v[40:43], v[176:179], v[208:211], v[40:43]
	v_mfma_f32_16x16x32_bf16 v[32:35], v[184:187], v[208:211], v[32:35]
	v_mfma_f32_16x16x32_bf16 v[24:27], v[176:179], v[216:219], v[24:27]
	v_mfma_f32_16x16x32_bf16 v[16:19], v[184:187], v[216:219], v[16:19]
	v_mfma_f32_16x16x32_bf16 v[8:11], v[176:179], v[224:227], v[8:11]
	v_mfma_f32_16x16x32_bf16 v[0:3], v[184:187], v[224:227], v[0:3]
	v_mfma_f32_16x16x32_bf16 v[56:59], v[180:183], v[196:199], v[56:59]
	v_mfma_f32_16x16x32_bf16 v[48:51], v[188:191], v[196:199], v[48:51]
	v_mfma_f32_16x16x32_bf16 v[40:43], v[180:183], v[212:215], v[40:43]
	v_mfma_f32_16x16x32_bf16 v[32:35], v[188:191], v[212:215], v[32:35]
	v_mfma_f32_16x16x32_bf16 v[24:27], v[180:183], v[220:223], v[24:27]
	v_mfma_f32_16x16x32_bf16 v[16:19], v[188:191], v[220:223], v[16:19]
	v_mfma_f32_16x16x32_bf16 v[8:11], v[180:183], v[228:231], v[8:11]
	v_mfma_f32_16x16x32_bf16 v[0:3], v[188:191], v[228:231], v[0:3]
	s_setprio 0
	s_barrier
; #define PG8_STAGE(bufoff, gbase, voff) do { _Pragma("unroll") for (int _i = 0; _i < 2; ++_i) \
;         __builtin_amdgcn_global_load_lds((const unsigned*)((const char*)(gbase) + (voff)[_i]), (PG8_LAS unsigned*)(lds + (bufoff) + ldsw + _i * 8192), 16, 0, 0); } while (0)
; #define PG8_LDA(dst, b, h) do { _Pragma("unroll") for (int m = 0; m < 4; ++m) _Pragma("unroll") for (int k = 0; k < 2; ++k) dst[m][k] = *(const PG8_LAS bf16x8*)(lds + PG8_SA(b, h) + aoff + m * 2048 + k * 1024); } while (0)
; #define PG8_LDB(dst, b, h) do { _Pragma("unroll") for (int n = 0; n < 2; ++n) _Pragma("unroll") for (int k = 0; k < 2; ++k) dst[n][k] = *(const PG8_LAS bf16x8*)(lds + PG8_SB(b, h) + boff + n * 2048 + k * 1024); } while (0)
; #define PG8_MMA(ai, bj, At, Bt) do { __builtin_amdgcn_s_setprio(1); _Pragma("unroll") for (int m = 0; m < 4; ++m) _Pragma("unroll") for (int n = 0; n < 2; ++n) _Pragma("unroll") for (int k = 0; k < 2; ++k) \
;         acc[ai][bj][m][n] = __builtin_amdgcn_mfma_f32_16x16x32_bf16(Bt[n][k], At[m][k], acc[ai][bj][m][n], 0, 0, 0); __builtin_amdgcn_s_setprio(0); } while (0)
; #define PG8_WAIT_V(n) asm volatile("s_waitcnt vmcnt(" #n ")" ::: "memory")
; #define PG8_WAIT_L(n) asm volatile("s_waitcnt lgkmcnt(" #n ")" ::: "memory")
; #define PG8_BAR __builtin_amdgcn_s_barrier()
; #define PG8_SCHED __builtin_amdgcn_sched_barrier(0)
; template <class Epi, class Sched, bool ALIGN_EPI = false, bool SP2 = false>
; __device__ __forceinline__ void gemm_phase(PG8_LAS unsigned char* lds, const Gemm g, const Sched& S, const Epi& E) {
;     ...
;             PG8_LDB(B0, 1, 0); PG8_LDB(B1, 1, 1); PG8_SCHED; PG8_LDA(At, 1, 0); PG8_STAGE(PG8_SA(0, 1), a2 + hstep, voffA);
;             PG8_WAIT_V(8); PG8_WAIT_L(0); PG8_BAR; PG8_MMA(0, 0, At, B0); PG8_MMA(0, 1, At, B1); PG8_BAR; PG8_SCHED;
	s_add_i32 s67, 0, 0x18000
	v_add_u32_e32 v145, s67, v143
	s_add_i32 s68, 0, 0x1c000
	ds_read_b128 v[146:149], v145
	ds_read_b128 v[150:153], v145 offset:1024
	ds_read_b128 v[154:157], v145 offset:2048
	ds_read_b128 v[158:161], v145 offset:3072
	v_add_u32_e32 v145, s68, v143
	ds_read_b128 v[176:179], v145
	ds_read_b128 v[180:183], v145 offset:1024
	ds_read_b128 v[184:187], v145 offset:2048
	ds_read_b128 v[188:191], v145 offset:3072
	s_add_u32 s48, s48, 0x40000
	s_addc_u32 s49, s49, 0
	s_mov_b32 m0, s52
	v_lshl_add_u64 v[238:239], s[48:49], 0, v[136:137]
	ds_read_b128 v[192:195], v144 offset:32768
	ds_read_b128 v[196:199], v144 offset:33792
	ds_read_b128 v[208:211], v144 offset:34816
	ds_read_b128 v[212:215], v144 offset:35840
	ds_read_b128 v[216:219], v144 offset:36864
	ds_read_b128 v[220:223], v144 offset:37888
	ds_read_b128 v[224:227], v144 offset:38912
	ds_read_b128 v[228:231], v144 offset:39936
	global_load_lds_dwordx4 v[238:239], off
	v_lshl_add_u64 v[238:239], s[48:49], 0, v[132:133]
	s_mov_b32 m0, s53
	s_nop 0
	global_load_lds_dwordx4 v[238:239], off
	s_waitcnt vmcnt(8)
	s_waitcnt lgkmcnt(0)
	s_barrier
	s_setprio 1
	s_waitcnt lgkmcnt(0)
	v_mfma_f32_16x16x32_bf16 v[126:129], v[146:149], v[192:195], v[126:129]
	v_mfma_f32_16x16x32_bf16 v[118:121], v[154:157], v[192:195], v[118:121]
	v_mfma_f32_16x16x32_bf16 v[110:113], v[146:149], v[208:211], v[110:113]
	v_mfma_f32_16x16x32_bf16 v[102:105], v[154:157], v[208:211], v[102:105]
	v_mfma_f32_16x16x32_bf16 v[94:97], v[146:149], v[216:219], v[94:97]
	v_mfma_f32_16x16x32_bf16 v[86:89], v[154:157], v[216:219], v[86:89]
	v_mfma_f32_16x16x32_bf16 v[76:79], v[146:149], v[224:227], v[76:79]
	v_mfma_f32_16x16x32_bf16 v[68:71], v[154:157], v[224:227], v[68:71]
	v_mfma_f32_16x16x32_bf16 v[126:129], v[150:153], v[196:199], v[126:129]
	v_mfma_f32_16x16x32_bf16 v[118:121], v[158:161], v[196:199], v[118:121]
	v_mfma_f32_16x16x32_bf16 v[110:113], v[150:153], v[212:215], v[110:113]
	v_mfma_f32_16x16x32_bf16 v[102:105], v[158:161], v[212:215], v[102:105]
	v_mfma_f32_16x16x32_bf16 v[94:97], v[150:153], v[220:223], v[94:97]
	v_mfma_f32_16x16x32_bf16 v[86:89], v[158:161], v[220:223], v[86:89]
	v_mfma_f32_16x16x32_bf16 v[76:79], v[150:153], v[228:231], v[76:79]
	v_mfma_f32_16x16x32_bf16 v[68:71], v[158:161], v[228:231], v[68:71]
	s_setprio 0
	s_setprio 1
	v_mfma_f32_16x16x32_bf16 v[122:125], v[176:179], v[192:195], v[122:125]
	v_mfma_f32_16x16x32_bf16 v[114:117], v[184:187], v[192:195], v[114:117]
	v_mfma_f32_16x16x32_bf16 v[106:109], v[176:179], v[208:211], v[106:109]
	v_mfma_f32_16x16x32_bf16 v[98:101], v[184:187], v[208:211], v[98:101]
	v_mfma_f32_16x16x32_bf16 v[90:93], v[176:179], v[216:219], v[90:93]
	v_mfma_f32_16x16x32_bf16 v[82:85], v[184:187], v[216:219], v[82:85]
	v_mfma_f32_16x16x32_bf16 v[72:75], v[176:179], v[224:227], v[72:75]
	v_mfma_f32_16x16x32_bf16 v[64:67], v[184:187], v[224:227], v[64:67]
	v_mfma_f32_16x16x32_bf16 v[122:125], v[180:183], v[196:199], v[122:125]
	v_mfma_f32_16x16x32_bf16 v[114:117], v[188:191], v[196:199], v[114:117]
	v_mfma_f32_16x16x32_bf16 v[106:109], v[180:183], v[212:215], v[106:109]
	v_mfma_f32_16x16x32_bf16 v[98:101], v[188:191], v[212:215], v[98:101]
	v_mfma_f32_16x16x32_bf16 v[90:93], v[180:183], v[220:223], v[90:93]
	v_mfma_f32_16x16x32_bf16 v[82:85], v[188:191], v[220:223], v[82:85]
	v_mfma_f32_16x16x32_bf16 v[72:75], v[180:183], v[228:231], v[72:75]
	v_mfma_f32_16x16x32_bf16 v[64:67], v[188:191], v[228:231], v[64:67]
	s_setprio 0
	s_barrier
; #define PG8_STAGE(bufoff, gbase, voff) do { _Pragma("unroll") for (int _i = 0; _i < 2; ++_i) \
;         __builtin_amdgcn_global_load_lds((const unsigned*)((const char*)(gbase) + (voff)[_i]), (PG8_LAS unsigned*)(lds + (bufoff) + ldsw + _i * 8192), 16, 0, 0); } while (0)
; #define PG8_LDA(dst, b, h) do { _Pragma("unroll") for (int m = 0; m < 4; ++m) _Pragma("unroll") for (int k = 0; k < 2; ++k) dst[m][k] = *(const PG8_LAS bf16x8*)(lds + PG8_SA(b, h) + aoff + m * 2048 + k * 1024); } while (0)
; #define PG8_MMA(ai, bj, At, Bt) do { __builtin_amdgcn_s_setprio(1); _Pragma("unroll") for (int m = 0; m < 4; ++m) _Pragma("unroll") for (int n = 0; n < 2; ++n) _Pragma("unroll") for (int k = 0; k < 2; ++k) \
;         acc[ai][bj][m][n] = __builtin_amdgcn_mfma_f32_16x16x32_bf16(Bt[n][k], At[m][k], acc[ai][bj][m][n], 0, 0, 0); __builtin_amdgcn_s_setprio(0); } while (0)
; #define PG8_WAIT_V(n) asm volatile("s_waitcnt vmcnt(" #n ")" ::: "memory")
; #define PG8_WAIT_L(n) asm volatile("s_waitcnt lgkmcnt(" #n ")" ::: "memory")
; #define PG8_BAR __builtin_amdgcn_s_barrier()
; #define PG8_SCHED __builtin_amdgcn_sched_barrier(0)
; template <class Epi, class Sched, bool ALIGN_EPI = false, bool SP2 = false>
; __device__ __forceinline__ void gemm_phase(PG8_LAS unsigned char* lds, const Gemm g, const Sched& S, const Epi& E) {
;     ...
;             PG8_LDA(At, 1, 1); PG8_STAGE(PG8_SB(1, 0), b3, voffB); PG8_STAGE(PG8_SB(1, 1), b3 + hstep, voffB); PG8_STAGE(PG8_SA(1, 0), a3, voffA);
;             PG8_WAIT_V(8); PG8_WAIT_L(0); PG8_BAR; PG8_MMA(1, 0, At, B0); PG8_MMA(1, 1, At, B1); PG8_BAR; PG8_SCHED;
	s_add_i32 s48, s67, s39
	v_lshl_add_u64 v[200:201], v[200:201], 0, s[40:41]
	s_mov_b32 m0, s48
	ds_read_b128 v[192:195], v144 offset:49152
	ds_read_b128 v[196:199], v144 offset:50176
	ds_read_b128 v[208:211], v144 offset:51200
	ds_read_b128 v[212:215], v144 offset:52224
	ds_read_b128 v[216:219], v144 offset:53248
	ds_read_b128 v[220:223], v144 offset:54272
	ds_read_b128 v[224:227], v144 offset:55296
	ds_read_b128 v[228:231], v144 offset:56320
	global_load_lds_dwordx4 v[200:201], off
	s_add_i32 m0, s48, 0x2000
	s_add_u32 s46, s46, 0x40080
	v_lshl_add_u64 v[200:201], v[232:233], 0, s[40:41]
	s_addc_u32 s47, s47, 0
	s_add_i32 s48, s68, s39
	global_load_lds_dwordx4 v[200:201], off
	v_lshl_add_u64 v[200:201], s[46:47], 0, v[134:135]
	s_mov_b32 m0, s48
	s_nop 0
	global_load_lds_dwordx4 v[200:201], off
	v_lshl_add_u64 v[200:201], s[46:47], 0, v[130:131]
	s_add_i32 m0, s48, 0x2000
	s_nop 0
	global_load_lds_dwordx4 v[200:201], off
	v_lshl_add_u64 v[200:201], v[234:235], 0, s[40:41]
	s_mov_b32 m0, s56
	s_nop 0
	global_load_lds_dwordx4 v[200:201], off
	v_lshl_add_u64 v[200:201], v[236:237], 0, s[40:41]
	s_mov_b32 m0, s57
	s_nop 0
	global_load_lds_dwordx4 v[200:201], off
	s_waitcnt vmcnt(8)
	s_waitcnt lgkmcnt(0)
	s_barrier
	s_setprio 1
	s_waitcnt lgkmcnt(0)
	v_mfma_f32_16x16x32_bf16 v[60:63], v[146:149], v[192:195], v[60:63]
	v_mfma_f32_16x16x32_bf16 v[52:55], v[154:157], v[192:195], v[52:55]
	v_mfma_f32_16x16x32_bf16 v[44:47], v[146:149], v[208:211], v[44:47]
	v_mfma_f32_16x16x32_bf16 v[36:39], v[154:157], v[208:211], v[36:39]
	v_mfma_f32_16x16x32_bf16 v[28:31], v[146:149], v[216:219], v[28:31]
	v_mfma_f32_16x16x32_bf16 v[20:23], v[154:157], v[216:219], v[20:23]
	v_mfma_f32_16x16x32_bf16 v[12:15], v[146:149], v[224:227], v[12:15]
	v_mfma_f32_16x16x32_bf16 v[4:7], v[154:157], v[224:227], v[4:7]
	v_mfma_f32_16x16x32_bf16 v[60:63], v[150:153], v[196:199], v[60:63]
	v_mfma_f32_16x16x32_bf16 v[52:55], v[158:161], v[196:199], v[52:55]
	v_mfma_f32_16x16x32_bf16 v[44:47], v[150:153], v[212:215], v[44:47]
	v_mfma_f32_16x16x32_bf16 v[36:39], v[158:161], v[212:215], v[36:39]
	v_mfma_f32_16x16x32_bf16 v[28:31], v[150:153], v[220:223], v[28:31]
	v_mfma_f32_16x16x32_bf16 v[20:23], v[158:161], v[220:223], v[20:23]
	v_mfma_f32_16x16x32_bf16 v[12:15], v[150:153], v[228:231], v[12:15]
	v_mfma_f32_16x16x32_bf16 v[4:7], v[158:161], v[228:231], v[4:7]
	s_setprio 0
	s_setprio 1
	v_mfma_f32_16x16x32_bf16 v[56:59], v[176:179], v[192:195], v[56:59]
	v_mfma_f32_16x16x32_bf16 v[48:51], v[184:187], v[192:195], v[48:51]
	v_mfma_f32_16x16x32_bf16 v[40:43], v[176:179], v[208:211], v[40:43]
	v_mfma_f32_16x16x32_bf16 v[32:35], v[184:187], v[208:211], v[32:35]
	v_mfma_f32_16x16x32_bf16 v[24:27], v[176:179], v[216:219], v[24:27]
	v_mfma_f32_16x16x32_bf16 v[16:19], v[184:187], v[216:219], v[16:19]
	v_mfma_f32_16x16x32_bf16 v[8:11], v[176:179], v[224:227], v[8:11]
	v_mfma_f32_16x16x32_bf16 v[0:3], v[184:187], v[224:227], v[0:3]
	v_mfma_f32_16x16x32_bf16 v[56:59], v[180:183], v[196:199], v[56:59]
	v_mfma_f32_16x16x32_bf16 v[48:51], v[188:191], v[196:199], v[48:51]
	v_mfma_f32_16x16x32_bf16 v[40:43], v[180:183], v[212:215], v[40:43]
	v_mfma_f32_16x16x32_bf16 v[32:35], v[188:191], v[212:215], v[32:35]
	v_mfma_f32_16x16x32_bf16 v[24:27], v[180:183], v[220:223], v[24:27]
	v_mfma_f32_16x16x32_bf16 v[16:19], v[188:191], v[220:223], v[16:19]
	v_mfma_f32_16x16x32_bf16 v[8:11], v[180:183], v[228:231], v[8:11]
	v_mfma_f32_16x16x32_bf16 v[0:3], v[188:191], v[228:231], v[0:3]
	s_setprio 0
	s_barrier
	s_add_i32 s66, s66, 2
	s_add_u32 s44, s44, 0x100
	s_addc_u32 s45, s45, 0
	s_add_u32 s64, s64, 0x100
	s_addc_u32 s65, s65, 0
	s_cmp_gt_u32 s66, 13
	s_cbranch_scc0 .LBB0_110
